# ph_post V-transpose part rewritten: two items' 2-byte gathers in flight per trip
# speedup vs baseline: 1.0555x; 1.0039x over previous
.LBB0_889:
	v_readlane_b32 s66, v254, 5
	s_cmpk_gt_i32 s1, 0x1fff
	v_readlane_b32 s67, v254, 6
	v_readlane_b32 s33, v255, 8
	s_mov_b32 s69, 0x800000
	s_cbranch_scc1 .LBB0_900
	s_and_b32 s2, s1, 7
	v_lshlrev_b32_e32 v3, 1, v58
	v_lshlrev_b32_e32 v4, 4, v58
	s_mov_b32 s3, s1
	s_cmp_gt_u32 s2, 5
	s_cbranch_scc1 .Lvt_p
	s_lshl_b32 s0, s2, 7
	s_add_i32 s0, s0, 0xc00
	v_add_u32_e32 v3, s0, v3
.Lvt_u_pair:
	s_and_b32 s33, s3, -8
	s_movk_i32 s42, 0x800
	s_cmpk_gt_i32 s33, 0xfff
	s_cselect_b32 s42, s42, 0x100
	s_add_i32 s0, s42, -1
	s_andn2_b32 s43, s33, s0
	s_and_b32 s44, s33, s0
	s_mul_i32 s0, s33, 0x1400
	s_add_u32 s4, s46, s0
	s_addc_u32 s5, s47, 0
	s_add_u32 s6, s4, 0x1400
	s_addc_u32 s7, s5, 0
	s_add_u32 s8, s6, 0x1400
	s_addc_u32 s9, s7, 0
	s_add_u32 s10, s8, 0x1400
	s_addc_u32 s11, s9, 0
	s_add_u32 s12, s10, 0x1400
	s_addc_u32 s13, s11, 0
	s_add_u32 s14, s12, 0x1400
	s_addc_u32 s15, s13, 0
	s_add_u32 s16, s14, 0x1400
	s_addc_u32 s17, s15, 0
	s_add_u32 s18, s16, 0x1400
	s_addc_u32 s19, s17, 0
	global_load_ushort v8, v3, s[4:5]
	global_load_ushort v9, v3, s[6:7]
	global_load_ushort v10, v3, s[8:9]
	global_load_ushort v11, v3, s[10:11]
	global_load_ushort v12, v3, s[12:13]
	global_load_ushort v13, v3, s[14:15]
	global_load_ushort v14, v3, s[16:17]
	global_load_ushort v15, v3, s[18:19]
	s_mul_i32 s0, s43, 0x300
	s_mul_i32 s33, s2, s42
	s_lshl_b32 s33, s33, 7
	s_add_i32 s0, s0, s33
	s_lshr_b32 s33, s44, 3
	s_lshl_b32 s33, s33, 10
	s_add_i32 s0, s0, s33
	s_add_u32 s38, s50, 0xa400000
	s_addc_u32 s39, s51, 0
	s_add_u32 s38, s38, s0
	s_addc_u32 s39, s39, 0
	s_add_i32 s4, s3, s68
	s_cmpk_lt_i32 s4, 0x2000
	s_cbranch_scc0 .Lvt_u_noB
	s_and_b32 s33, s4, -8
	s_movk_i32 s42, 0x800
	s_cmpk_gt_i32 s33, 0xfff
	s_cselect_b32 s42, s42, 0x100
	s_add_i32 s0, s42, -1
	s_andn2_b32 s43, s33, s0
	s_and_b32 s44, s33, s0
	s_mul_i32 s0, s33, 0x1400
	s_add_u32 s20, s46, s0
	s_addc_u32 s21, s47, 0
	s_add_u32 s22, s20, 0x1400
	s_addc_u32 s23, s21, 0
	s_add_u32 s24, s22, 0x1400
	s_addc_u32 s25, s23, 0
	s_add_u32 s26, s24, 0x1400
	s_addc_u32 s27, s25, 0
	s_add_u32 s28, s26, 0x1400
	s_addc_u32 s29, s27, 0
	s_add_u32 s30, s28, 0x1400
	s_addc_u32 s31, s29, 0
	s_add_u32 s34, s30, 0x1400
	s_addc_u32 s35, s31, 0
	s_add_u32 s36, s34, 0x1400
	s_addc_u32 s37, s35, 0
	global_load_ushort v24, v3, s[20:21]
	global_load_ushort v25, v3, s[22:23]
	global_load_ushort v26, v3, s[24:25]
	global_load_ushort v27, v3, s[26:27]
	global_load_ushort v28, v3, s[28:29]
	global_load_ushort v29, v3, s[30:31]
	global_load_ushort v30, v3, s[34:35]
	global_load_ushort v31, v3, s[36:37]
	s_mul_i32 s0, s43, 0x300
	s_mul_i32 s33, s2, s42
	s_lshl_b32 s33, s33, 7
	s_add_i32 s0, s0, s33
	s_lshr_b32 s33, s44, 3
	s_lshl_b32 s33, s33, 10
	s_add_i32 s0, s0, s33
	s_add_u32 s40, s50, 0xa400000
	s_addc_u32 s41, s51, 0
	s_add_u32 s40, s40, s0
	s_addc_u32 s41, s41, 0
	s_waitcnt vmcnt(8)
	v_lshl_or_b32 v40, v9, 16, v8
	v_lshl_or_b32 v41, v11, 16, v10
	v_lshl_or_b32 v42, v13, 16, v12
	v_lshl_or_b32 v43, v15, 16, v14
	global_store_dwordx4 v4, v[40:43], s[38:39]
	s_waitcnt vmcnt(1)
	v_lshl_or_b32 v44, v25, 16, v24
	v_lshl_or_b32 v45, v27, 16, v26
	v_lshl_or_b32 v46, v29, 16, v28
	v_lshl_or_b32 v47, v31, 16, v30
	global_store_dwordx4 v4, v[44:47], s[40:41]
	s_branch .Lvt_u_next
.Lvt_u_noB:
	s_waitcnt vmcnt(0)
	v_lshl_or_b32 v40, v9, 16, v8
	v_lshl_or_b32 v41, v11, 16, v10
	v_lshl_or_b32 v42, v13, 16, v12
	v_lshl_or_b32 v43, v15, 16, v14
	global_store_dwordx4 v4, v[40:43], s[38:39]
.Lvt_u_next:
	s_lshl_b32 s0, s68, 1
	s_add_i32 s3, s3, s0
	s_cmpk_lt_i32 s3, 0x2000
	s_cbranch_scc1 .Lvt_u_pair
	s_branch .LBB0_900
.Lvt_p:
	s_add_i32 s2, s2, -6
	s_lshl_b32 s0, s2, 7
	s_add_i32 s0, s0, 0x300
	v_add_u32_e32 v3, s0, v3
.Lvt_p_pair:
	s_and_b32 s33, s3, -8
	s_movk_i32 s42, 0x800
	s_cmpk_gt_i32 s33, 0xfff
	s_cselect_b32 s42, s42, 0x100
	s_add_i32 s0, s42, -1
	s_andn2_b32 s43, s33, s0
	s_and_b32 s44, s33, s0
	s_lshl_b32 s0, s33, 10
	s_add_u32 s4, s50, 0xd800000
	s_addc_u32 s5, s51, 0
	s_add_u32 s4, s4, s0
	s_addc_u32 s5, s5, 0
	s_add_u32 s6, s4, 0x1000
	s_addc_u32 s7, s5, 0
	s_add_u32 s8, s4, 0x800000
	s_addc_u32 s9, s5, 0
	s_add_u32 s10, s8, 0x1000
	s_addc_u32 s11, s9, 0
	global_load_ushort v8, v3, s[4:5]
	global_load_ushort v9, v3, s[4:5] offset:1024
	global_load_ushort v10, v3, s[4:5] offset:2048
	global_load_ushort v11, v3, s[4:5] offset:3072
	global_load_ushort v12, v3, s[6:7]
	global_load_ushort v13, v3, s[6:7] offset:1024
	global_load_ushort v14, v3, s[6:7] offset:2048
	global_load_ushort v15, v3, s[6:7] offset:3072
	global_load_ushort v16, v3, s[8:9]
	global_load_ushort v17, v3, s[8:9] offset:1024
	global_load_ushort v18, v3, s[8:9] offset:2048
	global_load_ushort v19, v3, s[8:9] offset:3072
	global_load_ushort v20, v3, s[10:11]
	global_load_ushort v21, v3, s[10:11] offset:1024
	global_load_ushort v22, v3, s[10:11] offset:2048
	global_load_ushort v23, v3, s[10:11] offset:3072
	s_lshl_b32 s0, s43, 8
	s_mul_i32 s33, s2, s42
	s_lshl_b32 s33, s33, 7
	s_add_i32 s0, s0, s33
	s_lshr_b32 s33, s44, 3
	s_lshl_b32 s33, s33, 10
	s_add_i32 s0, s0, s33
	s_add_u32 s38, s50, 0xb200000
	s_addc_u32 s39, s51, 0
	s_add_u32 s38, s38, s0
	s_addc_u32 s39, s39, 0
	s_add_i32 s12, s3, s68
	s_cmpk_lt_i32 s12, 0x2000
	s_cbranch_scc0 .Lvt_p_noB
	s_and_b32 s33, s12, -8
	s_movk_i32 s42, 0x800
	s_cmpk_gt_i32 s33, 0xfff
	s_cselect_b32 s42, s42, 0x100
	s_add_i32 s0, s42, -1
	s_andn2_b32 s43, s33, s0
	s_and_b32 s44, s33, s0
	s_lshl_b32 s0, s33, 10
	s_add_u32 s20, s50, 0xd800000
	s_addc_u32 s21, s51, 0
	s_add_u32 s20, s20, s0
	s_addc_u32 s21, s21, 0
	s_add_u32 s22, s20, 0x1000
	s_addc_u32 s23, s21, 0
	s_add_u32 s24, s20, 0x800000
	s_addc_u32 s25, s21, 0
	s_add_u32 s26, s24, 0x1000
	s_addc_u32 s27, s25, 0
	global_load_ushort v24, v3, s[20:21]
	global_load_ushort v25, v3, s[20:21] offset:1024
	global_load_ushort v26, v3, s[20:21] offset:2048
	global_load_ushort v27, v3, s[20:21] offset:3072
	global_load_ushort v28, v3, s[22:23]
	global_load_ushort v29, v3, s[22:23] offset:1024
	global_load_ushort v30, v3, s[22:23] offset:2048
	global_load_ushort v31, v3, s[22:23] offset:3072
	global_load_ushort v32, v3, s[24:25]
	global_load_ushort v33, v3, s[24:25] offset:1024
	global_load_ushort v34, v3, s[24:25] offset:2048
	global_load_ushort v35, v3, s[24:25] offset:3072
	global_load_ushort v36, v3, s[26:27]
	global_load_ushort v37, v3, s[26:27] offset:1024
	global_load_ushort v38, v3, s[26:27] offset:2048
	global_load_ushort v39, v3, s[26:27] offset:3072
	s_lshl_b32 s0, s43, 8
	s_mul_i32 s33, s2, s42
	s_lshl_b32 s33, s33, 7
	s_add_i32 s0, s0, s33
	s_lshr_b32 s33, s44, 3
	s_lshl_b32 s33, s33, 10
	s_add_i32 s0, s0, s33
	s_add_u32 s40, s50, 0xb200000
	s_addc_u32 s41, s51, 0
	s_add_u32 s40, s40, s0
	s_addc_u32 s41, s41, 0
	s_waitcnt vmcnt(16)
	v_lshlrev_b32_e32 v8, 16, v8
	v_lshlrev_b32_e32 v9, 16, v9
	v_lshlrev_b32_e32 v10, 16, v10
	v_lshlrev_b32_e32 v11, 16, v11
	v_lshlrev_b32_e32 v12, 16, v12
	v_lshlrev_b32_e32 v13, 16, v13
	v_lshlrev_b32_e32 v14, 16, v14
	v_lshlrev_b32_e32 v15, 16, v15
	v_lshlrev_b32_e32 v16, 16, v16
	v_lshlrev_b32_e32 v17, 16, v17
	v_lshlrev_b32_e32 v18, 16, v18
	v_lshlrev_b32_e32 v19, 16, v19
	v_lshlrev_b32_e32 v20, 16, v20
	v_lshlrev_b32_e32 v21, 16, v21
	v_lshlrev_b32_e32 v22, 16, v22
	v_lshlrev_b32_e32 v23, 16, v23
	v_add_f32_e32 v8, v8, v16
	v_add_f32_e32 v9, v9, v17
	v_add_f32_e32 v10, v10, v18
	v_add_f32_e32 v11, v11, v19
	v_add_f32_e32 v12, v12, v20
	v_add_f32_e32 v13, v13, v21
	v_add_f32_e32 v14, v14, v22
	v_add_f32_e32 v15, v15, v23
	v_cvt_pk_bf16_f32 v40, v8, v9
	v_cvt_pk_bf16_f32 v41, v10, v11
	v_cvt_pk_bf16_f32 v42, v12, v13
	v_cvt_pk_bf16_f32 v43, v14, v15
	global_store_dwordx4 v4, v[40:43], s[38:39]
	s_waitcnt vmcnt(1)
	v_lshlrev_b32_e32 v24, 16, v24
	v_lshlrev_b32_e32 v25, 16, v25
	v_lshlrev_b32_e32 v26, 16, v26
	v_lshlrev_b32_e32 v27, 16, v27
	v_lshlrev_b32_e32 v28, 16, v28
	v_lshlrev_b32_e32 v29, 16, v29
	v_lshlrev_b32_e32 v30, 16, v30
	v_lshlrev_b32_e32 v31, 16, v31
	v_lshlrev_b32_e32 v32, 16, v32
	v_lshlrev_b32_e32 v33, 16, v33
	v_lshlrev_b32_e32 v34, 16, v34
	v_lshlrev_b32_e32 v35, 16, v35
	v_lshlrev_b32_e32 v36, 16, v36
	v_lshlrev_b32_e32 v37, 16, v37
	v_lshlrev_b32_e32 v38, 16, v38
	v_lshlrev_b32_e32 v39, 16, v39
	v_add_f32_e32 v24, v24, v32
	v_add_f32_e32 v25, v25, v33
	v_add_f32_e32 v26, v26, v34
	v_add_f32_e32 v27, v27, v35
	v_add_f32_e32 v28, v28, v36
	v_add_f32_e32 v29, v29, v37
	v_add_f32_e32 v30, v30, v38
	v_add_f32_e32 v31, v31, v39
	v_cvt_pk_bf16_f32 v44, v24, v25
	v_cvt_pk_bf16_f32 v45, v26, v27
	v_cvt_pk_bf16_f32 v46, v28, v29
	v_cvt_pk_bf16_f32 v47, v30, v31
	global_store_dwordx4 v4, v[44:47], s[40:41]
	s_branch .Lvt_p_next
.Lvt_p_noB:
	s_waitcnt vmcnt(0)
	v_lshlrev_b32_e32 v8, 16, v8
	v_lshlrev_b32_e32 v9, 16, v9
	v_lshlrev_b32_e32 v10, 16, v10
	v_lshlrev_b32_e32 v11, 16, v11
	v_lshlrev_b32_e32 v12, 16, v12
	v_lshlrev_b32_e32 v13, 16, v13
	v_lshlrev_b32_e32 v14, 16, v14
	v_lshlrev_b32_e32 v15, 16, v15
	v_lshlrev_b32_e32 v16, 16, v16
	v_lshlrev_b32_e32 v17, 16, v17
	v_lshlrev_b32_e32 v18, 16, v18
	v_lshlrev_b32_e32 v19, 16, v19
	v_lshlrev_b32_e32 v20, 16, v20
	v_lshlrev_b32_e32 v21, 16, v21
	v_lshlrev_b32_e32 v22, 16, v22
	v_lshlrev_b32_e32 v23, 16, v23
	v_add_f32_e32 v8, v8, v16
	v_add_f32_e32 v9, v9, v17
	v_add_f32_e32 v10, v10, v18
	v_add_f32_e32 v11, v11, v19
	v_add_f32_e32 v12, v12, v20
	v_add_f32_e32 v13, v13, v21
	v_add_f32_e32 v14, v14, v22
	v_add_f32_e32 v15, v15, v23
	v_cvt_pk_bf16_f32 v40, v8, v9
	v_cvt_pk_bf16_f32 v41, v10, v11
	v_cvt_pk_bf16_f32 v42, v12, v13
	v_cvt_pk_bf16_f32 v43, v14, v15
	global_store_dwordx4 v4, v[40:43], s[38:39]
.Lvt_p_next:
	s_lshl_b32 s0, s68, 1
	s_add_i32 s3, s3, s0
	s_cmpk_lt_i32 s3, 0x2000
	s_cbranch_scc1 .Lvt_p_pair
